# main G1 tile header no longer drains the previous tile's H stores before the K loop (vmcnt(0) kept only on first-tile entry)
# baseline (speedup 1.0000x reference)
.LBB0_51:
	v_readlane_b32 s12, v254, 61
	v_mov_b32_e32 v161, v1
	v_readlane_b32 s13, v254, 62
	s_and_b32 s8, s6, 3
	s_add_i32 m0, s69, 0x18000
	v_lshl_add_u64 v[2:3], v[2:3], 0, s[48:49]
	v_lshl_add_u64 v[12:13], s[12:13], 0, v[160:161]
	v_mov_b32_e32 v157, v1
	s_lshl_b32 s97, s1, 6
	s_lshl_b32 s1, s1, 13
	s_lshl_b32 s9, s8, 12
	s_waitcnt vmcnt(2)
	s_barrier
	global_load_lds_dwordx4 v[2:3], off
	v_lshl_add_u64 v[2:3], v[4:5], 0, s[48:49]
	s_add_i32 m0, s69, 0x1a000
	s_add_i32 s74, s69, 0x8000
	s_add_i32 s75, s69, 0xa000
	v_lshl_add_u64 v[14:15], s[12:13], 0, v[156:157]
	global_load_lds_dwordx4 v[2:3], off
	v_lshl_add_u64 v[2:3], v[12:13], 0, s[48:49]
	s_mov_b32 m0, s74
	s_add_u32 s6, s4, 0x40080
	global_load_lds_dwordx4 v[2:3], off
	v_lshl_add_u64 v[2:3], v[14:15], 0, s[48:49]
	s_mov_b32 m0, s75
	s_addc_u32 s7, s5, 0
	global_load_lds_dwordx4 v[2:3], off
	s_add_i32 m0, s69, 0x1c000
	v_lshl_add_u64 v[2:3], s[6:7], 0, v[158:159]
	global_load_lds_dwordx4 v[2:3], off
	v_lshl_add_u64 v[2:3], s[6:7], 0, v[154:155]
	s_add_i32 m0, s69, 0x1e000
	v_and_b32_e32 v163, 15, v0
	global_load_lds_dwordx4 v[2:3], off
	v_bfe_u32 v2, v0, 4, 2
	v_lshlrev_b32_e32 v4, 4, v2
	v_lshlrev_b32_e32 v0, 2, v0
	v_lshlrev_b32_e32 v3, 3, v2
	v_lshl_or_b32 v4, v163, 6, v4
	v_and_b32_e32 v0, 32, v0
	s_cmpk_lt_u32 s0, 0x100
	v_bitop3_b32 v5, v4, s1, v0 bitop3:0xde
	s_cselect_b64 s[6:7], -1, 0
	v_lshl_or_b32 v164, s8, 5, v3
	s_bitcmp1_b32 s0, 6
	v_readlane_b32 s0, v252, 4
	v_bitop3_b32 v198, v4, s9, v0 bitop3:0xde
	v_lshlrev_b32_e32 v0, 1, v164
	v_readlane_b32 s1, v252, 5
	v_cmp_eq_u32_e64 s[38:39], 0, v2
	v_cmp_gt_u32_e64 s[40:41], 2, v2
	v_lshl_add_u64 v[166:167], s[0:1], 0, v[0:1]
	v_lshlrev_b32_e32 v0, 14, v10
	v_and_b32_e32 v0, 0xffff8000, v0
	v_lshl_add_u32 v0, v9, 11, v0
	v_and_b32_e32 v2, 1, v10
	v_lshl_or_b32 v0, v2, 6, v0
	v_lshl_add_u32 v168, v11, 1, v0
	v_lshlrev_b32_e32 v0, 14, v6
	v_and_b32_e32 v0, 0xffff8000, v0
	s_waitcnt vmcnt(6)
	v_lshl_add_u32 v0, v7, 11, v0
	v_and_b32_e32 v2, 1, v6
	v_readlane_b32 s0, v254, 59
	v_writelane_b32 v255, s6, 4
	v_lshl_or_b32 v0, v2, 6, v0
	v_readlane_b32 s1, v254, 60
	v_or_b32_e32 v162, 0x80, v163
	v_writelane_b32 v255, s7, 5
	v_mov_b32_e32 v165, v1
	s_cselect_b64 s[90:91], -1, 0
	s_mov_b32 s88, 0
	v_or_b32_e32 v199, 0x1000, v163
	v_mov_b32_e32 v169, v1
	v_lshl_add_u32 v170, v8, 1, v0
	v_mov_b32_e32 v171, v1
	v_add_u32_e32 v200, 0, v5
	v_readlane_b32 s8, v254, 50
	s_mov_b32 s10, s0
	s_mov_b64 s[0:1], s[12:13]
	s_barrier
	s_waitcnt vmcnt(0)
	s_branch .LBB0_54

.LBB0_56:
	s_ashr_i32 s95, s94, 31
	s_lshl_b64 s[6:7], s[94:95], 19
	v_readlane_b32 s9, v253, 5
	s_add_u32 s80, s9, s6
	v_readlane_b32 s6, v253, 6
	s_addc_u32 s81, s6, s7
	s_and_b64 s[6:7], s[42:43], exec
	s_cselect_b32 s9, s81, s1
	s_cselect_b32 s11, s80, s0
	s_ashr_i32 s93, s92, 31
	s_lshl_b64 s[6:7], s[92:93], 19
	v_readlane_b32 s12, v253, 61
	s_add_u32 s82, s12, s6
	v_readlane_b32 s6, v253, 62
	s_addc_u32 s83, s6, s7
	s_and_b64 s[6:7], s[42:43], exec
	s_cselect_b32 s12, s83, s5
	s_cselect_b32 s13, s82, s4
	s_add_u32 s0, s0, 0x40080
	s_addc_u32 s1, s1, 0
	s_add_u32 s14, s4, 0x100
	v_mov_b32_e32 v2, 0
	s_addc_u32 s15, s5, 0
	s_mov_b32 s16, -2
	v_mov_b32_e32 v3, v2
	v_mov_b32_e32 v4, v2
	v_mov_b32_e32 v5, v2
	v_mov_b32_e32 v6, v2
	v_mov_b32_e32 v7, v2
	v_mov_b32_e32 v8, v2
	v_mov_b32_e32 v9, v2
	v_mov_b32_e32 v26, v2
	v_mov_b32_e32 v27, v2
	v_mov_b32_e32 v28, v2
	v_mov_b32_e32 v29, v2
	v_mov_b32_e32 v30, v2
	v_mov_b32_e32 v31, v2
	v_mov_b32_e32 v32, v2
	v_mov_b32_e32 v33, v2
	v_mov_b32_e32 v50, v2
	v_mov_b32_e32 v51, v2
	v_mov_b32_e32 v52, v2
	v_mov_b32_e32 v53, v2
	v_mov_b32_e32 v54, v2
	v_mov_b32_e32 v55, v2
	v_mov_b32_e32 v56, v2
	v_mov_b32_e32 v57, v2
	v_mov_b32_e32 v66, v2
	v_mov_b32_e32 v67, v2
	v_mov_b32_e32 v68, v2
	v_mov_b32_e32 v69, v2
	v_mov_b32_e32 v70, v2
	v_mov_b32_e32 v71, v2
	v_mov_b32_e32 v72, v2
	v_mov_b32_e32 v73, v2
	v_mov_b32_e32 v10, v2
	v_mov_b32_e32 v11, v2
	v_mov_b32_e32 v12, v2
	v_mov_b32_e32 v13, v2
	v_mov_b32_e32 v14, v2
	v_mov_b32_e32 v15, v2
	v_mov_b32_e32 v16, v2
	v_mov_b32_e32 v17, v2
	v_mov_b32_e32 v42, v2
	v_mov_b32_e32 v43, v2
	v_mov_b32_e32 v44, v2
	v_mov_b32_e32 v45, v2
	v_mov_b32_e32 v46, v2
	v_mov_b32_e32 v47, v2
	v_mov_b32_e32 v48, v2
	v_mov_b32_e32 v49, v2
	v_mov_b32_e32 v58, v2
	v_mov_b32_e32 v59, v2
	v_mov_b32_e32 v60, v2
	v_mov_b32_e32 v61, v2
	v_mov_b32_e32 v62, v2
	v_mov_b32_e32 v63, v2
	v_mov_b32_e32 v64, v2
	v_mov_b32_e32 v65, v2
	v_mov_b32_e32 v74, v2
	v_mov_b32_e32 v75, v2
	v_mov_b32_e32 v76, v2
	v_mov_b32_e32 v77, v2
	v_mov_b32_e32 v78, v2
	v_mov_b32_e32 v79, v2
	v_mov_b32_e32 v80, v2
	v_mov_b32_e32 v81, v2
	v_mov_b32_e32 v82, v2
	v_mov_b32_e32 v83, v2
	v_mov_b32_e32 v84, v2
	v_mov_b32_e32 v85, v2
	v_mov_b32_e32 v86, v2
	v_mov_b32_e32 v87, v2
	v_mov_b32_e32 v88, v2
	v_mov_b32_e32 v89, v2
	v_mov_b32_e32 v98, v2
	v_mov_b32_e32 v99, v2
	v_mov_b32_e32 v100, v2
	v_mov_b32_e32 v101, v2
	v_mov_b32_e32 v102, v2
	v_mov_b32_e32 v103, v2
	v_mov_b32_e32 v104, v2
	v_mov_b32_e32 v105, v2
	v_mov_b32_e32 v114, v2
	v_mov_b32_e32 v115, v2
	v_mov_b32_e32 v116, v2
	v_mov_b32_e32 v117, v2
	v_mov_b32_e32 v118, v2
	v_mov_b32_e32 v119, v2
	v_mov_b32_e32 v120, v2
	v_mov_b32_e32 v121, v2
	v_mov_b32_e32 v130, v2
	v_mov_b32_e32 v131, v2
	v_mov_b32_e32 v132, v2
	v_mov_b32_e32 v133, v2
	v_mov_b32_e32 v134, v2
	v_mov_b32_e32 v135, v2
	v_mov_b32_e32 v136, v2
	v_mov_b32_e32 v137, v2
	v_mov_b32_e32 v90, v2
	v_mov_b32_e32 v91, v2
	v_mov_b32_e32 v92, v2
	v_mov_b32_e32 v93, v2
	v_mov_b32_e32 v94, v2
	v_mov_b32_e32 v95, v2
	v_mov_b32_e32 v96, v2
	v_mov_b32_e32 v97, v2
	v_mov_b32_e32 v106, v2
	v_mov_b32_e32 v107, v2
	v_mov_b32_e32 v108, v2
	v_mov_b32_e32 v109, v2
	v_mov_b32_e32 v110, v2
	v_mov_b32_e32 v111, v2
	v_mov_b32_e32 v112, v2
	v_mov_b32_e32 v113, v2
	v_mov_b32_e32 v122, v2
	v_mov_b32_e32 v123, v2
	v_mov_b32_e32 v124, v2
	v_mov_b32_e32 v125, v2
	v_mov_b32_e32 v126, v2
	v_mov_b32_e32 v127, v2
	v_mov_b32_e32 v128, v2
	v_mov_b32_e32 v129, v2
	v_mov_b32_e32 v138, v2
	v_mov_b32_e32 v139, v2
	v_mov_b32_e32 v140, v2
	v_mov_b32_e32 v141, v2
	v_mov_b32_e32 v142, v2
	v_mov_b32_e32 v143, v2
	v_mov_b32_e32 v144, v2
	v_mov_b32_e32 v145, v2
.LBB0_57:
	s_add_u32 s4, s0, 0xfffc0080
	s_addc_u32 s5, s1, -1
	s_add_i32 s17, 0, 0x10000
	s_cmp_eq_u32 s16, 12
	s_cselect_b32 s7, s9, s5
	s_cselect_b32 s6, s11, s4
	v_add_u32_e32 v0, s17, v198
	s_cselect_b32 s5, s12, s15
	s_cselect_b32 s4, s13, s14
	s_add_i32 s20, 0, 0x14000
	ds_read_b128 v[18:21], v0
	ds_read_b128 v[22:25], v0 offset:1024
	ds_read_b128 v[34:37], v0 offset:2048
	ds_read_b128 v[38:41], v0 offset:3072
	v_add_u32_e32 v0, s20, v198
	ds_read_b128 v[146:149], v0
	ds_read_b128 v[150:153], v0 offset:1024
	ds_read_b128 v[172:175], v0 offset:2048
	ds_read_b128 v[176:179], v0 offset:3072
	v_lshl_add_u64 v[188:189], s[0:1], 0, v[168:169]
	s_add_i32 m0, s69, 0xc000
	ds_read_b128 v[180:183], v200
	ds_read_b128 v[184:187], v200 offset:1024
	ds_read_b128 v[202:205], v200 offset:2048
	ds_read_b128 v[206:209], v200 offset:3072
	ds_read_b128 v[210:213], v200 offset:4096
	ds_read_b128 v[214:217], v200 offset:5120
	ds_read_b128 v[218:221], v200 offset:6144
	ds_read_b128 v[234:237], v200 offset:7168
	global_load_lds_dwordx4 v[188:189], off
	v_lshl_add_u64 v[188:189], s[0:1], 0, v[170:171]
	s_add_i32 m0, s69, 0xe000
	s_nop 0
	global_load_lds_dwordx4 v[188:189], off
	s_waitcnt vmcnt(8)
	s_waitcnt lgkmcnt(0)
	s_barrier
	s_setprio 1
	s_waitcnt lgkmcnt(0)
	v_mfma_f32_16x16x32_bf16 v[142:145], v[18:21], v[180:183], v[142:145]
	v_mfma_f32_16x16x32_bf16 v[138:141], v[34:37], v[180:183], v[138:141]
	v_mfma_f32_16x16x32_bf16 v[126:129], v[18:21], v[202:205], v[126:129]
	v_mfma_f32_16x16x32_bf16 v[122:125], v[34:37], v[202:205], v[122:125]
	v_mfma_f32_16x16x32_bf16 v[110:113], v[18:21], v[210:213], v[110:113]
	v_mfma_f32_16x16x32_bf16 v[106:109], v[34:37], v[210:213], v[106:109]
	v_mfma_f32_16x16x32_bf16 v[94:97], v[18:21], v[218:221], v[94:97]
	v_mfma_f32_16x16x32_bf16 v[90:93], v[34:37], v[218:221], v[90:93]
	v_mfma_f32_16x16x32_bf16 v[142:145], v[22:25], v[184:187], v[142:145]
	v_mfma_f32_16x16x32_bf16 v[138:141], v[38:41], v[184:187], v[138:141]
	v_mfma_f32_16x16x32_bf16 v[126:129], v[22:25], v[206:209], v[126:129]
	v_mfma_f32_16x16x32_bf16 v[122:125], v[38:41], v[206:209], v[122:125]
	v_mfma_f32_16x16x32_bf16 v[110:113], v[22:25], v[214:217], v[110:113]
	v_mfma_f32_16x16x32_bf16 v[106:109], v[38:41], v[214:217], v[106:109]
	v_mfma_f32_16x16x32_bf16 v[94:97], v[22:25], v[234:237], v[94:97]
	v_mfma_f32_16x16x32_bf16 v[90:93], v[38:41], v[234:237], v[90:93]
	s_setprio 0
	s_setprio 1
	v_mfma_f32_16x16x32_bf16 v[134:137], v[146:149], v[180:183], v[134:137]
	v_mfma_f32_16x16x32_bf16 v[130:133], v[172:175], v[180:183], v[130:133]
	v_mfma_f32_16x16x32_bf16 v[118:121], v[146:149], v[202:205], v[118:121]
	v_mfma_f32_16x16x32_bf16 v[114:117], v[172:175], v[202:205], v[114:117]
	v_mfma_f32_16x16x32_bf16 v[102:105], v[146:149], v[210:213], v[102:105]
	v_mfma_f32_16x16x32_bf16 v[98:101], v[172:175], v[210:213], v[98:101]
	v_mfma_f32_16x16x32_bf16 v[86:89], v[146:149], v[218:221], v[86:89]
	v_mfma_f32_16x16x32_bf16 v[82:85], v[172:175], v[218:221], v[82:85]
	v_mfma_f32_16x16x32_bf16 v[134:137], v[150:153], v[184:187], v[134:137]
	v_mfma_f32_16x16x32_bf16 v[130:133], v[176:179], v[184:187], v[130:133]
	v_mfma_f32_16x16x32_bf16 v[118:121], v[150:153], v[206:209], v[118:121]
	v_mfma_f32_16x16x32_bf16 v[114:117], v[176:179], v[206:209], v[114:117]
	v_mfma_f32_16x16x32_bf16 v[102:105], v[150:153], v[214:217], v[102:105]
	v_mfma_f32_16x16x32_bf16 v[98:101], v[176:179], v[214:217], v[98:101]
	v_mfma_f32_16x16x32_bf16 v[86:89], v[150:153], v[234:237], v[86:89]
	v_mfma_f32_16x16x32_bf16 v[82:85], v[176:179], v[234:237], v[82:85]
	s_setprio 0
	s_barrier
	s_add_i32 s17, s17, s87
	v_lshl_add_u64 v[188:189], s[4:5], 0, v[158:159]
	s_mov_b32 m0, s17
	ds_read_b128 v[180:183], v200 offset:16384
	ds_read_b128 v[184:187], v200 offset:17408
	ds_read_b128 v[202:205], v200 offset:18432
	ds_read_b128 v[206:209], v200 offset:19456
	ds_read_b128 v[210:213], v200 offset:20480
	ds_read_b128 v[214:217], v200 offset:21504
	ds_read_b128 v[218:221], v200 offset:22528
	ds_read_b128 v[234:237], v200 offset:23552
	global_load_lds_dwordx4 v[188:189], off
	s_add_i32 m0, s17, 0x2000
	s_add_u32 s18, s4, 0x40000
	v_lshl_add_u64 v[222:223], s[4:5], 0, v[154:155]
	s_addc_u32 s19, s5, 0
	s_add_i32 s17, s20, s87
	global_load_lds_dwordx4 v[222:223], off
	v_lshl_add_u64 v[238:239], s[18:19], 0, v[158:159]
	s_mov_b32 m0, s17
	v_lshl_add_u64 v[240:241], s[6:7], 0, v[156:157]
	global_load_lds_dwordx4 v[238:239], off
	v_lshl_add_u64 v[238:239], s[18:19], 0, v[154:155]
	s_add_i32 m0, s17, 0x2000
	s_nop 0
	global_load_lds_dwordx4 v[238:239], off
	v_lshl_add_u64 v[238:239], s[6:7], 0, v[160:161]
	s_mov_b32 m0, s69
	s_nop 0
	global_load_lds_dwordx4 v[238:239], off
	s_mov_b32 m0, s76
	s_nop 0
	global_load_lds_dwordx4 v[240:241], off
	s_waitcnt vmcnt(8)
	s_waitcnt lgkmcnt(0)
	s_barrier
	s_setprio 1
	s_waitcnt lgkmcnt(0)
	v_mfma_f32_16x16x32_bf16 v[78:81], v[18:21], v[180:183], v[78:81]
	v_mfma_f32_16x16x32_bf16 v[74:77], v[34:37], v[180:183], v[74:77]
	v_mfma_f32_16x16x32_bf16 v[62:65], v[18:21], v[202:205], v[62:65]
	v_mfma_f32_16x16x32_bf16 v[58:61], v[34:37], v[202:205], v[58:61]
	v_mfma_f32_16x16x32_bf16 v[46:49], v[18:21], v[210:213], v[46:49]
	v_mfma_f32_16x16x32_bf16 v[42:45], v[34:37], v[210:213], v[42:45]
	v_mfma_f32_16x16x32_bf16 v[14:17], v[18:21], v[218:221], v[14:17]
	v_mfma_f32_16x16x32_bf16 v[10:13], v[34:37], v[218:221], v[10:13]
	v_mfma_f32_16x16x32_bf16 v[78:81], v[22:25], v[184:187], v[78:81]
	v_mfma_f32_16x16x32_bf16 v[74:77], v[38:41], v[184:187], v[74:77]
	v_mfma_f32_16x16x32_bf16 v[62:65], v[22:25], v[206:209], v[62:65]
	v_mfma_f32_16x16x32_bf16 v[58:61], v[38:41], v[206:209], v[58:61]
	v_mfma_f32_16x16x32_bf16 v[46:49], v[22:25], v[214:217], v[46:49]
	v_mfma_f32_16x16x32_bf16 v[42:45], v[38:41], v[214:217], v[42:45]
	v_mfma_f32_16x16x32_bf16 v[14:17], v[22:25], v[234:237], v[14:17]
	v_mfma_f32_16x16x32_bf16 v[10:13], v[38:41], v[234:237], v[10:13]
	s_setprio 0
	s_setprio 1
	v_mfma_f32_16x16x32_bf16 v[30:33], v[146:149], v[210:213], v[30:33]
	v_mfma_f32_16x16x32_bf16 v[26:29], v[172:175], v[210:213], v[26:29]
	v_mfma_f32_16x16x32_bf16 v[6:9], v[146:149], v[218:221], v[6:9]
	v_mfma_f32_16x16x32_bf16 v[2:5], v[172:175], v[218:221], v[2:5]
	v_mfma_f32_16x16x32_bf16 v[18:21], v[146:149], v[180:183], v[70:73]
	v_mfma_f32_16x16x32_bf16 v[22:25], v[172:175], v[180:183], v[66:69]
	v_mfma_f32_16x16x32_bf16 v[34:37], v[146:149], v[202:205], v[54:57]
	v_mfma_f32_16x16x32_bf16 v[38:41], v[172:175], v[202:205], v[50:53]
	v_mfma_f32_16x16x32_bf16 v[30:33], v[150:153], v[214:217], v[30:33]
	v_mfma_f32_16x16x32_bf16 v[26:29], v[176:179], v[214:217], v[26:29]
	v_mfma_f32_16x16x32_bf16 v[6:9], v[150:153], v[234:237], v[6:9]
	v_mfma_f32_16x16x32_bf16 v[2:5], v[176:179], v[234:237], v[2:5]
	v_mfma_f32_16x16x32_bf16 v[18:21], v[150:153], v[184:187], v[18:21]
	v_mfma_f32_16x16x32_bf16 v[22:25], v[176:179], v[184:187], v[22:25]
	v_mfma_f32_16x16x32_bf16 v[34:37], v[150:153], v[206:209], v[34:37]
	v_mfma_f32_16x16x32_bf16 v[38:41], v[176:179], v[206:209], v[38:41]
	s_setprio 0
	s_barrier
	s_add_i32 s17, 0, 0x18000
	v_add_u32_e32 v0, s17, v198
	s_add_i32 s18, 0, 0x1c000
	ds_read_b128 v[50:53], v0
	ds_read_b128 v[54:57], v0 offset:1024
	ds_read_b128 v[66:69], v0 offset:2048
	ds_read_b128 v[70:73], v0 offset:3072
	v_add_u32_e32 v0, s18, v198
	ds_read_b128 v[146:149], v0
	ds_read_b128 v[150:153], v0 offset:1024
	ds_read_b128 v[172:175], v0 offset:2048
	ds_read_b128 v[176:179], v0 offset:3072
	s_add_u32 s6, s6, 0x40000
	s_addc_u32 s7, s7, 0
	s_mov_b32 m0, s77
	v_lshl_add_u64 v[242:243], s[6:7], 0, v[160:161]
	ds_read_b128 v[180:183], v200 offset:32768
	ds_read_b128 v[184:187], v200 offset:33792
	ds_read_b128 v[202:205], v200 offset:34816
	ds_read_b128 v[206:209], v200 offset:35840
	ds_read_b128 v[210:213], v200 offset:36864
	ds_read_b128 v[214:217], v200 offset:37888
	ds_read_b128 v[218:221], v200 offset:38912
	ds_read_b128 v[234:237], v200 offset:39936
	global_load_lds_dwordx4 v[242:243], off
	v_lshl_add_u64 v[242:243], s[6:7], 0, v[156:157]
	s_mov_b32 m0, s96
	s_nop 0
	global_load_lds_dwordx4 v[242:243], off
	s_waitcnt vmcnt(8)
	s_waitcnt lgkmcnt(0)
	s_barrier
	s_setprio 1
	s_waitcnt lgkmcnt(0)
	v_mfma_f32_16x16x32_bf16 v[142:145], v[50:53], v[180:183], v[142:145]
	v_mfma_f32_16x16x32_bf16 v[138:141], v[66:69], v[180:183], v[138:141]
	v_mfma_f32_16x16x32_bf16 v[126:129], v[50:53], v[202:205], v[126:129]
	v_mfma_f32_16x16x32_bf16 v[122:125], v[66:69], v[202:205], v[122:125]
	v_mfma_f32_16x16x32_bf16 v[110:113], v[50:53], v[210:213], v[110:113]
	v_mfma_f32_16x16x32_bf16 v[106:109], v[66:69], v[210:213], v[106:109]
	v_mfma_f32_16x16x32_bf16 v[94:97], v[50:53], v[218:221], v[94:97]
	v_mfma_f32_16x16x32_bf16 v[90:93], v[66:69], v[218:221], v[90:93]
	v_mfma_f32_16x16x32_bf16 v[142:145], v[54:57], v[184:187], v[142:145]
	v_mfma_f32_16x16x32_bf16 v[138:141], v[70:73], v[184:187], v[138:141]
	v_mfma_f32_16x16x32_bf16 v[126:129], v[54:57], v[206:209], v[126:129]
	v_mfma_f32_16x16x32_bf16 v[122:125], v[70:73], v[206:209], v[122:125]
	v_mfma_f32_16x16x32_bf16 v[110:113], v[54:57], v[214:217], v[110:113]
	v_mfma_f32_16x16x32_bf16 v[106:109], v[70:73], v[214:217], v[106:109]
	v_mfma_f32_16x16x32_bf16 v[94:97], v[54:57], v[234:237], v[94:97]
	v_mfma_f32_16x16x32_bf16 v[90:93], v[70:73], v[234:237], v[90:93]
	s_setprio 0
	s_setprio 1
	v_mfma_f32_16x16x32_bf16 v[134:137], v[146:149], v[180:183], v[134:137]
	v_mfma_f32_16x16x32_bf16 v[130:133], v[172:175], v[180:183], v[130:133]
	v_mfma_f32_16x16x32_bf16 v[118:121], v[146:149], v[202:205], v[118:121]
	v_mfma_f32_16x16x32_bf16 v[114:117], v[172:175], v[202:205], v[114:117]
	v_mfma_f32_16x16x32_bf16 v[102:105], v[146:149], v[210:213], v[102:105]
	v_mfma_f32_16x16x32_bf16 v[98:101], v[172:175], v[210:213], v[98:101]
	v_mfma_f32_16x16x32_bf16 v[86:89], v[146:149], v[218:221], v[86:89]
	v_mfma_f32_16x16x32_bf16 v[82:85], v[172:175], v[218:221], v[82:85]
	v_mfma_f32_16x16x32_bf16 v[134:137], v[150:153], v[184:187], v[134:137]
	v_mfma_f32_16x16x32_bf16 v[130:133], v[176:179], v[184:187], v[130:133]
	v_mfma_f32_16x16x32_bf16 v[118:121], v[150:153], v[206:209], v[118:121]
	v_mfma_f32_16x16x32_bf16 v[114:117], v[176:179], v[206:209], v[114:117]
	v_mfma_f32_16x16x32_bf16 v[102:105], v[150:153], v[214:217], v[102:105]
	v_mfma_f32_16x16x32_bf16 v[98:101], v[176:179], v[214:217], v[98:101]
	v_mfma_f32_16x16x32_bf16 v[86:89], v[150:153], v[234:237], v[86:89]
	v_mfma_f32_16x16x32_bf16 v[82:85], v[176:179], v[234:237], v[82:85]
	s_setprio 0
	s_barrier
	s_add_i32 s6, s17, s87
	v_lshl_add_u64 v[188:189], v[188:189], 0, s[48:49]
	s_mov_b32 m0, s6
	ds_read_b128 v[180:183], v200 offset:49152
	ds_read_b128 v[184:187], v200 offset:50176
	ds_read_b128 v[202:205], v200 offset:51200
	ds_read_b128 v[206:209], v200 offset:52224
	ds_read_b128 v[210:213], v200 offset:53248
	ds_read_b128 v[214:217], v200 offset:54272
	ds_read_b128 v[218:221], v200 offset:55296
	ds_read_b128 v[234:237], v200 offset:56320
	global_load_lds_dwordx4 v[188:189], off
	s_add_i32 m0, s6, 0x2000
	s_add_u32 s4, s4, 0x40080
	v_lshl_add_u64 v[188:189], v[222:223], 0, s[48:49]
	s_addc_u32 s5, s5, 0
	s_add_i32 s6, s18, s87
	global_load_lds_dwordx4 v[188:189], off
	v_lshl_add_u64 v[188:189], s[4:5], 0, v[158:159]
	s_mov_b32 m0, s6
	s_nop 0
	global_load_lds_dwordx4 v[188:189], off
	v_lshl_add_u64 v[188:189], s[4:5], 0, v[154:155]
	s_add_i32 m0, s6, 0x2000
	s_nop 0
	global_load_lds_dwordx4 v[188:189], off
	v_lshl_add_u64 v[188:189], v[238:239], 0, s[48:49]
	s_mov_b32 m0, s74
	s_nop 0
	global_load_lds_dwordx4 v[188:189], off
	v_lshl_add_u64 v[188:189], v[240:241], 0, s[48:49]
	s_mov_b32 m0, s75
	s_nop 0
	global_load_lds_dwordx4 v[188:189], off
	s_waitcnt vmcnt(8)
	s_waitcnt lgkmcnt(0)
	s_barrier
	s_setprio 1
	s_waitcnt lgkmcnt(0)
	v_mfma_f32_16x16x32_bf16 v[78:81], v[50:53], v[180:183], v[78:81]
	v_mfma_f32_16x16x32_bf16 v[74:77], v[66:69], v[180:183], v[74:77]
	v_mfma_f32_16x16x32_bf16 v[62:65], v[50:53], v[202:205], v[62:65]
	v_mfma_f32_16x16x32_bf16 v[58:61], v[66:69], v[202:205], v[58:61]
	v_mfma_f32_16x16x32_bf16 v[46:49], v[50:53], v[210:213], v[46:49]
	v_mfma_f32_16x16x32_bf16 v[42:45], v[66:69], v[210:213], v[42:45]
	v_mfma_f32_16x16x32_bf16 v[14:17], v[50:53], v[218:221], v[14:17]
	v_mfma_f32_16x16x32_bf16 v[10:13], v[66:69], v[218:221], v[10:13]
	v_mfma_f32_16x16x32_bf16 v[78:81], v[54:57], v[184:187], v[78:81]
	v_mfma_f32_16x16x32_bf16 v[74:77], v[70:73], v[184:187], v[74:77]
	v_mfma_f32_16x16x32_bf16 v[62:65], v[54:57], v[206:209], v[62:65]
	v_mfma_f32_16x16x32_bf16 v[58:61], v[70:73], v[206:209], v[58:61]
	v_mfma_f32_16x16x32_bf16 v[46:49], v[54:57], v[214:217], v[46:49]
	v_mfma_f32_16x16x32_bf16 v[42:45], v[70:73], v[214:217], v[42:45]
	v_mfma_f32_16x16x32_bf16 v[14:17], v[54:57], v[234:237], v[14:17]
	v_mfma_f32_16x16x32_bf16 v[10:13], v[70:73], v[234:237], v[10:13]
	s_setprio 0
	s_setprio 1
	v_mfma_f32_16x16x32_bf16 v[18:21], v[146:149], v[180:183], v[18:21]
	v_mfma_f32_16x16x32_bf16 v[70:73], v[150:153], v[184:187], v[18:21]
	v_mfma_f32_16x16x32_bf16 v[18:21], v[172:175], v[180:183], v[22:25]
	v_mfma_f32_16x16x32_bf16 v[66:69], v[176:179], v[184:187], v[18:21]
	v_mfma_f32_16x16x32_bf16 v[18:21], v[146:149], v[202:205], v[34:37]
	v_mfma_f32_16x16x32_bf16 v[54:57], v[150:153], v[206:209], v[18:21]
	v_mfma_f32_16x16x32_bf16 v[18:21], v[172:175], v[202:205], v[38:41]
	v_mfma_f32_16x16x32_bf16 v[50:53], v[176:179], v[206:209], v[18:21]
	v_mfma_f32_16x16x32_bf16 v[18:21], v[146:149], v[210:213], v[30:33]
	v_mfma_f32_16x16x32_bf16 v[30:33], v[150:153], v[214:217], v[18:21]
	v_mfma_f32_16x16x32_bf16 v[18:21], v[172:175], v[210:213], v[26:29]
	v_mfma_f32_16x16x32_bf16 v[6:9], v[146:149], v[218:221], v[6:9]
	v_mfma_f32_16x16x32_bf16 v[2:5], v[172:175], v[218:221], v[2:5]
	v_mfma_f32_16x16x32_bf16 v[26:29], v[176:179], v[214:217], v[18:21]
	v_mfma_f32_16x16x32_bf16 v[6:9], v[150:153], v[234:237], v[6:9]
	v_mfma_f32_16x16x32_bf16 v[2:5], v[176:179], v[234:237], v[2:5]
	s_setprio 0
	s_barrier
	s_add_i32 s16, s16, 2
	s_add_u32 s0, s0, 0x100
	s_addc_u32 s1, s1, 0
	s_add_u32 s14, s14, 0x100
	s_addc_u32 s15, s15, 0
	s_cmp_gt_u32 s16, 13
	s_cbranch_scc0 .LBB0_57
	v_readlane_b32 s0, v255, 4
	v_readlane_b32 s1, v255, 5
	s_and_b64 vcc, exec, s[0:1]
	s_cbranch_vccz .LBB0_60
	s_barrier
